# v11 plus non-temporal (nt) stores in the input-projection epilogues
# speedup vs baseline: 1.0041x; 1.0041x over previous
; __device__ __forceinline__ float bf_lo(unsigned w) { return __uint_as_float(w << 16); }
;     __device__ __forceinline__ void operator()(const f32x4 (&acc)[2][2][4][2], const pg8::Unit& u, int wr, int wc, int fr_, int fq_) const {
;     ...
;             const int row0 = u.pm * 256 + wr * 64 + fr, col0 = colt + wc * 32 + 8 * fq;
; #pragma unroll
;             for (int ai = 0; ai < 2; ++ai)
; #pragma unroll
;                 for (int m = 0; m < 4; ++m) { const size_t roff = (size_t)(row0 + ai * 128 + m * 16) * ld + col0;
; #pragma unroll
;                     for (int bj = 0; bj < 2; ++bj) { f32x4 v0 = acc[ai][bj][m][0], v1 = acc[ai][bj][m][1]; const size_t off = roff + bj * 128;
;                         float v[8] = {v0[0], v0[1], v0[2], v0[3], v1[0], v1[1], v1[2], v1[3]};
;                         if constexpr (MODE == EPI_INPROJ) {
; #pragma unroll
;                             for (int i = 0; i < 8; ++i) v[i] *= sc;
;                         }
;                         if constexpr (MODE == EPI_GLU) {
;                             const u32x4 yg = *(const u32x4*)(X1 + off); const u32x4 zs = *(const u32x4*)(base + off);
; #pragma unroll
;                             for (int i = 0; i < 4; ++i) { v[2 * i] = bf_lo(yg[i]) * sigm(v[2 * i] * sc_all) * silu(bf_lo(zs[i])); v[2 * i + 1] = bf_hi(yg[i]) * sigm(v[2 * i + 1] * sc_all) * silu(bf_hi(zs[i])); }
;                         }
;                         if constexpr (MODE == EPI_MRG_A) {
;                             const u32x4 ga = *(const u32x4*)(base + off);
; #pragma unroll
;                             for (int i = 0; i < 4; ++i) { v[2 * i] *= sigm(bf_lo(ga[i])); v[2 * i + 1] *= sigm(bf_hi(ga[i])); }
;                         }
;                         if constexpr (MODE == EPI_MRG_B) {
;                             const u32x4 ga = *(const u32x4*)(base + off); const u32x4 gs = *(const u32x4*)(X1 + off);
; #pragma unroll
;                             for (int i = 0; i < 4; ++i) { v[2 * i] = bf_lo(ga[i]) + sigm(bf_lo(gs[i])) * v[2 * i]; v[2 * i + 1] = bf_hi(ga[i]) + sigm(bf_hi(gs[i])) * v[2 * i + 1]; }
;                         }
;                         if constexpr (MODE == EPI_OUT_A) {
;                             const f32x4 r0 = *(const f32x4*)(res + off), r1 = *(const f32x4*)(res + off + 4); const u32x4 pl = *(const u32x4*)(X1 + off);
;                             f32x4 o0, o1;
.LBB0_132:
	s_lshl_b32 s10, s20, 8
	s_add_i32 s10, s10, s63
	v_and_or_b32 v3, v0, 15, s10
	v_lshrrev_b32_e32 v0, 1, v0
	v_and_or_b32 v0, v0, 24, s4
	v_or_b32_e32 v162, s80, v0
	v_lshl_add_u64 v[0:1], v[162:163], 1, s[22:23]
	v_mad_i64_i32 v[4:5], s[20:21], s38, v3, 0
	v_lshl_add_u64 v[8:9], v[4:5], 1, v[0:1]
	v_mul_f32_e32 v4, v156, v2
	v_mul_f32_e32 v5, v157, v2
	v_mul_f32_e32 v6, v158, v2
	v_mul_f32_e32 v7, v159, v2
	v_cvt_pk_bf16_f32 v4, v4, v5
	v_mul_f32_e32 v10, v152, v2
	v_mul_f32_e32 v11, v153, v2
	v_mul_f32_e32 v12, v154, v2
	v_mul_f32_e32 v13, v155, v2
	v_cvt_pk_bf16_f32 v5, v6, v7
	v_cvt_pk_bf16_f32 v6, v10, v11
	v_cvt_pk_bf16_f32 v7, v12, v13
	flat_store_dwordx4 v[8:9], v[4:7] nt
	v_mul_f32_e32 v10, v136, v2
	v_mul_f32_e32 v11, v137, v2
	v_mul_f32_e32 v4, v144, v2
	v_mul_f32_e32 v5, v145, v2
	v_mul_f32_e32 v6, v146, v2
	v_mul_f32_e32 v7, v147, v2
	v_cvt_pk_bf16_f32 v4, v4, v5
	v_mul_f32_e32 v12, v138, v2
	v_mul_f32_e32 v13, v139, v2
	v_cvt_pk_bf16_f32 v5, v6, v7
	v_cvt_pk_bf16_f32 v6, v10, v11
	v_cvt_pk_bf16_f32 v7, v12, v13
	flat_store_dwordx4 v[8:9], v[4:7] offset:256 nt
	v_mul_f32_e32 v10, v140, v2
	v_mul_f32_e32 v11, v141, v2
	v_or_b32_e32 v4, 16, v3
	v_mad_i64_i32 v[4:5], s[20:21], s38, v4, 0
	v_lshl_add_u64 v[8:9], v[4:5], 1, v[0:1]
	v_mul_f32_e32 v4, v148, v2
	v_mul_f32_e32 v5, v149, v2
	v_mul_f32_e32 v6, v150, v2
	v_mul_f32_e32 v7, v151, v2
	v_cvt_pk_bf16_f32 v4, v4, v5
	v_mul_f32_e32 v12, v142, v2
	v_mul_f32_e32 v13, v143, v2
	v_cvt_pk_bf16_f32 v5, v6, v7
	v_cvt_pk_bf16_f32 v6, v10, v11
	v_cvt_pk_bf16_f32 v7, v12, v13
	flat_store_dwordx4 v[8:9], v[4:7] nt
	v_mul_f32_e32 v10, v120, v2
	v_mul_f32_e32 v11, v121, v2
	v_mul_f32_e32 v4, v128, v2
	v_mul_f32_e32 v5, v129, v2
	v_mul_f32_e32 v6, v130, v2
	v_mul_f32_e32 v7, v131, v2
	v_cvt_pk_bf16_f32 v4, v4, v5
	v_mul_f32_e32 v12, v122, v2
	v_mul_f32_e32 v13, v123, v2
	v_cvt_pk_bf16_f32 v5, v6, v7
	v_cvt_pk_bf16_f32 v6, v10, v11
	v_cvt_pk_bf16_f32 v7, v12, v13
	flat_store_dwordx4 v[8:9], v[4:7] offset:256 nt
	v_mul_f32_e32 v10, v124, v2
	v_mul_f32_e32 v11, v125, v2
	v_or_b32_e32 v4, 32, v3
	v_mad_i64_i32 v[4:5], s[20:21], s38, v4, 0
	v_lshl_add_u64 v[8:9], v[4:5], 1, v[0:1]
	v_mul_f32_e32 v4, v132, v2
	v_mul_f32_e32 v5, v133, v2
	v_mul_f32_e32 v6, v134, v2
	v_mul_f32_e32 v7, v135, v2
	v_cvt_pk_bf16_f32 v4, v4, v5
	v_mul_f32_e32 v12, v126, v2
	v_mul_f32_e32 v13, v127, v2
	v_cvt_pk_bf16_f32 v5, v6, v7
	v_cvt_pk_bf16_f32 v6, v10, v11
	v_cvt_pk_bf16_f32 v7, v12, v13
	flat_store_dwordx4 v[8:9], v[4:7] nt
	v_mul_f32_e32 v10, v104, v2
	v_mul_f32_e32 v11, v105, v2
	v_mul_f32_e32 v4, v112, v2
	v_mul_f32_e32 v5, v113, v2
	v_mul_f32_e32 v6, v114, v2
	v_mul_f32_e32 v7, v115, v2
	v_cvt_pk_bf16_f32 v4, v4, v5
	v_mul_f32_e32 v12, v106, v2
	v_mul_f32_e32 v13, v107, v2
	v_cvt_pk_bf16_f32 v5, v6, v7
	v_cvt_pk_bf16_f32 v6, v10, v11
	v_cvt_pk_bf16_f32 v7, v12, v13
	flat_store_dwordx4 v[8:9], v[4:7] offset:256 nt
	v_mul_f32_e32 v10, v108, v2
	v_mul_f32_e32 v11, v109, v2
	v_or_b32_e32 v4, 48, v3
	v_mad_i64_i32 v[4:5], s[20:21], s38, v4, 0
	v_lshl_add_u64 v[8:9], v[4:5], 1, v[0:1]
	v_mul_f32_e32 v4, v116, v2
	v_mul_f32_e32 v5, v117, v2
	v_mul_f32_e32 v6, v118, v2
	v_mul_f32_e32 v7, v119, v2
	v_cvt_pk_bf16_f32 v4, v4, v5
	v_mul_f32_e32 v12, v110, v2
	v_mul_f32_e32 v13, v111, v2
	v_cvt_pk_bf16_f32 v5, v6, v7
	v_cvt_pk_bf16_f32 v6, v10, v11
	v_cvt_pk_bf16_f32 v7, v12, v13
	flat_store_dwordx4 v[8:9], v[4:7] nt
	v_mul_f32_e32 v10, v96, v2
	v_mul_f32_e32 v11, v97, v2
	v_mul_f32_e32 v4, v100, v2
	v_mul_f32_e32 v5, v101, v2
	v_mul_f32_e32 v6, v102, v2
	v_mul_f32_e32 v7, v103, v2
	v_cvt_pk_bf16_f32 v4, v4, v5
	v_mul_f32_e32 v12, v98, v2
	v_mul_f32_e32 v13, v99, v2
	v_cvt_pk_bf16_f32 v5, v6, v7
	v_cvt_pk_bf16_f32 v6, v10, v11
	v_cvt_pk_bf16_f32 v7, v12, v13
; __device__ __forceinline__ float bf_lo(unsigned w) { return __uint_as_float(w << 16); }
;     __device__ __forceinline__ void operator()(const f32x4 (&acc)[2][2][4][2], const pg8::Unit& u, int wr, int wc, int fr_, int fq_) const {
;     ...
;             const int row0 = u.pm * 256 + wr * 64 + fr, col0 = colt + wc * 32 + 8 * fq;
; #pragma unroll
;             for (int ai = 0; ai < 2; ++ai)
; #pragma unroll
;                 for (int m = 0; m < 4; ++m) { const size_t roff = (size_t)(row0 + ai * 128 + m * 16) * ld + col0;
; #pragma unroll
;                     for (int bj = 0; bj < 2; ++bj) { f32x4 v0 = acc[ai][bj][m][0], v1 = acc[ai][bj][m][1]; const size_t off = roff + bj * 128;
;                         float v[8] = {v0[0], v0[1], v0[2], v0[3], v1[0], v1[1], v1[2], v1[3]};
;                         if constexpr (MODE == EPI_INPROJ) {
; #pragma unroll
;                             for (int i = 0; i < 8; ++i) v[i] *= sc;
;                         }
;                         if constexpr (MODE == EPI_GLU) {
;                             const u32x4 yg = *(const u32x4*)(X1 + off); const u32x4 zs = *(const u32x4*)(base + off);
; #pragma unroll
;                             for (int i = 0; i < 4; ++i) { v[2 * i] = bf_lo(yg[i]) * sigm(v[2 * i] * sc_all) * silu(bf_lo(zs[i])); v[2 * i + 1] = bf_hi(yg[i]) * sigm(v[2 * i + 1] * sc_all) * silu(bf_hi(zs[i])); }
;                         }
;                         if constexpr (MODE == EPI_MRG_A) {
;                             const u32x4 ga = *(const u32x4*)(base + off);
; #pragma unroll
;                             for (int i = 0; i < 4; ++i) { v[2 * i] *= sigm(bf_lo(ga[i])); v[2 * i + 1] *= sigm(bf_hi(ga[i])); }
;                         }
;                         if constexpr (MODE == EPI_MRG_B) {
;                             const u32x4 ga = *(const u32x4*)(base + off); const u32x4 gs = *(const u32x4*)(X1 + off);
; #pragma unroll
;                             for (int i = 0; i < 4; ++i) { v[2 * i] = bf_lo(ga[i]) + sigm(bf_lo(gs[i])) * v[2 * i]; v[2 * i + 1] = bf_hi(ga[i]) + sigm(bf_hi(gs[i])) * v[2 * i + 1]; }
;                         }
;                         if constexpr (MODE == EPI_OUT_A) {
;                             const f32x4 r0 = *(const f32x4*)(res + off), r1 = *(const f32x4*)(res + off + 4); const u32x4 pl = *(const u32x4*)(X1 + off);
;                             f32x4 o0, o1;
	flat_store_dwordx4 v[8:9], v[4:7] offset:256 nt
	v_mul_f32_e32 v10, v88, v2
	v_mul_f32_e32 v11, v89, v2
	v_add_u32_e32 v4, 0x80, v3
	v_mad_i64_i32 v[4:5], s[20:21], s38, v4, 0
	v_lshl_add_u64 v[8:9], v[4:5], 1, v[0:1]
	v_mul_f32_e32 v4, v92, v2
	v_mul_f32_e32 v5, v93, v2
	v_mul_f32_e32 v6, v94, v2
	v_mul_f32_e32 v7, v95, v2
	v_cvt_pk_bf16_f32 v4, v4, v5
	v_mul_f32_e32 v12, v90, v2
	v_mul_f32_e32 v13, v91, v2
	v_cvt_pk_bf16_f32 v5, v6, v7
	v_cvt_pk_bf16_f32 v6, v10, v11
	v_cvt_pk_bf16_f32 v7, v12, v13
	flat_store_dwordx4 v[8:9], v[4:7] nt
	v_mul_f32_e32 v10, v72, v2
	v_mul_f32_e32 v11, v73, v2
	v_mul_f32_e32 v4, v80, v2
	v_mul_f32_e32 v5, v81, v2
	v_mul_f32_e32 v6, v82, v2
	v_mul_f32_e32 v7, v83, v2
	v_cvt_pk_bf16_f32 v4, v4, v5
	v_mul_f32_e32 v12, v74, v2
	v_mul_f32_e32 v13, v75, v2
	v_cvt_pk_bf16_f32 v5, v6, v7
	v_cvt_pk_bf16_f32 v6, v10, v11
	v_cvt_pk_bf16_f32 v7, v12, v13
	flat_store_dwordx4 v[8:9], v[4:7] offset:256 nt
	v_mul_f32_e32 v10, v76, v2
	v_mul_f32_e32 v11, v77, v2
	v_add_u32_e32 v4, 0x90, v3
	v_mad_i64_i32 v[4:5], s[20:21], s38, v4, 0
	v_lshl_add_u64 v[8:9], v[4:5], 1, v[0:1]
	v_mul_f32_e32 v4, v84, v2
	v_mul_f32_e32 v5, v85, v2
	v_mul_f32_e32 v6, v86, v2
	v_mul_f32_e32 v7, v87, v2
	v_cvt_pk_bf16_f32 v4, v4, v5
	v_mul_f32_e32 v12, v78, v2
	v_mul_f32_e32 v13, v79, v2
	v_cvt_pk_bf16_f32 v5, v6, v7
	v_cvt_pk_bf16_f32 v6, v10, v11
	v_cvt_pk_bf16_f32 v7, v12, v13
	flat_store_dwordx4 v[8:9], v[4:7] nt
	v_mul_f32_e32 v10, v56, v2
	v_mul_f32_e32 v11, v57, v2
	v_mul_f32_e32 v4, v64, v2
	v_mul_f32_e32 v5, v65, v2
	v_mul_f32_e32 v6, v66, v2
	v_mul_f32_e32 v7, v67, v2
	v_cvt_pk_bf16_f32 v4, v4, v5
	v_mul_f32_e32 v12, v58, v2
	v_mul_f32_e32 v13, v59, v2
	v_cvt_pk_bf16_f32 v5, v6, v7
	v_cvt_pk_bf16_f32 v6, v10, v11
	v_cvt_pk_bf16_f32 v7, v12, v13
	flat_store_dwordx4 v[8:9], v[4:7] offset:256 nt
	v_mul_f32_e32 v10, v60, v2
	v_mul_f32_e32 v11, v61, v2
	v_add_u32_e32 v4, 0xa0, v3
	v_mad_i64_i32 v[4:5], s[20:21], s38, v4, 0
	v_lshl_add_u64 v[8:9], v[4:5], 1, v[0:1]
	v_mul_f32_e32 v4, v68, v2
	v_mul_f32_e32 v5, v69, v2
	v_mul_f32_e32 v6, v70, v2
	v_mul_f32_e32 v7, v71, v2
	v_cvt_pk_bf16_f32 v4, v4, v5
	v_cvt_pk_bf16_f32 v5, v6, v7
	v_mul_f32_e32 v12, v62, v2
	v_mul_f32_e32 v13, v63, v2
	v_cvt_pk_bf16_f32 v6, v10, v11
	v_cvt_pk_bf16_f32 v7, v12, v13
	flat_store_dwordx4 v[8:9], v[4:7] nt
	v_add_u32_e32 v3, 0xb0, v3
	v_mul_f32_e32 v10, v40, v2
	v_mul_f32_e32 v4, v48, v2
	v_mul_f32_e32 v5, v49, v2
	v_mul_f32_e32 v6, v50, v2
	v_mul_f32_e32 v7, v51, v2
	v_cvt_pk_bf16_f32 v4, v4, v5
	v_cvt_pk_bf16_f32 v5, v6, v7
	v_mul_f32_e32 v11, v41, v2
	v_mul_f32_e32 v12, v42, v2
	v_mul_f32_e32 v13, v43, v2
	v_cvt_pk_bf16_f32 v6, v10, v11
	v_cvt_pk_bf16_f32 v7, v12, v13
	flat_store_dwordx4 v[8:9], v[4:7] offset:256 nt
	v_mul_f32_e32 v10, v46, v2
	v_mul_f32_e32 v11, v47, v2
	v_mad_i64_i32 v[4:5], s[20:21], s38, v3, 0
	v_lshl_add_u64 v[8:9], v[4:5], 1, v[0:1]
	v_mul_f32_e32 v0, v52, v2
	v_mul_f32_e32 v1, v53, v2
	v_mul_f32_e32 v3, v54, v2
	v_mul_f32_e32 v5, v55, v2
	v_mul_f32_e32 v6, v44, v2
	v_mul_f32_e32 v7, v45, v2
	v_cvt_pk_bf16_f32 v4, v0, v1
	v_cvt_pk_bf16_f32 v5, v3, v5
	v_cvt_pk_bf16_f32 v6, v6, v7
	v_cvt_pk_bf16_f32 v7, v10, v11
	v_mul_f32_e32 v0, v36, v2
	v_mul_f32_e32 v1, v37, v2
	v_mul_f32_e32 v3, v38, v2
	s_andn2_b64 vcc, exec, s[36:37]
	s_mov_b64 s[20:21], -1
	flat_store_dwordx4 v[8:9], v[4:7] nt
	v_mul_f32_e32 v10, v35, v2
	v_cvt_pk_bf16_f32 v0, v0, v1
	s_nop 0
	v_mul_f32_e32 v4, v39, v2
	v_mul_f32_e32 v5, v32, v2
	v_mul_f32_e32 v6, v33, v2
	v_mul_f32_e32 v7, v34, v2
	v_cvt_pk_bf16_f32 v1, v3, v4
	v_cvt_pk_bf16_f32 v2, v5, v6
	v_cvt_pk_bf16_f32 v3, v7, v10
	flat_store_dwordx4 v[8:9], v[0:3] offset:256 nt
	s_cbranch_vccnz .LBB0_115
	s_andn2_b64 vcc, exec, s[6:7]
	s_cbranch_vccnz .LBB0_114
	s_barrier
	s_branch .LBB0_114

; __device__ __forceinline__ float bf_lo(unsigned w) { return __uint_as_float(w << 16); }
;     __device__ __forceinline__ void operator()(const f32x4 (&acc)[2][2][4][2], const pg8::Unit& u, int wr, int wc, int fr_, int fq_) const {
;     ...
;             const int row0 = u.pm * 256 + wr * 64 + fr, col0 = colt + wc * 32 + 8 * fq;
; #pragma unroll
;             for (int ai = 0; ai < 2; ++ai)
; #pragma unroll
;                 for (int m = 0; m < 4; ++m) { const size_t roff = (size_t)(row0 + ai * 128 + m * 16) * ld + col0;
; #pragma unroll
;                     for (int bj = 0; bj < 2; ++bj) { f32x4 v0 = acc[ai][bj][m][0], v1 = acc[ai][bj][m][1]; const size_t off = roff + bj * 128;
;                         float v[8] = {v0[0], v0[1], v0[2], v0[3], v1[0], v1[1], v1[2], v1[3]};
;                         if constexpr (MODE == EPI_INPROJ) {
; #pragma unroll
;                             for (int i = 0; i < 8; ++i) v[i] *= sc;
;                         }
;                         if constexpr (MODE == EPI_GLU) {
;                             const u32x4 yg = *(const u32x4*)(X1 + off); const u32x4 zs = *(const u32x4*)(base + off);
; #pragma unroll
;                             for (int i = 0; i < 4; ++i) { v[2 * i] = bf_lo(yg[i]) * sigm(v[2 * i] * sc_all) * silu(bf_lo(zs[i])); v[2 * i + 1] = bf_hi(yg[i]) * sigm(v[2 * i + 1] * sc_all) * silu(bf_hi(zs[i])); }
;                         }
;                         if constexpr (MODE == EPI_MRG_A) {
;                             const u32x4 ga = *(const u32x4*)(base + off);
; #pragma unroll
;                             for (int i = 0; i < 4; ++i) { v[2 * i] *= sigm(bf_lo(ga[i])); v[2 * i + 1] *= sigm(bf_hi(ga[i])); }
;                         }
;                         if constexpr (MODE == EPI_MRG_B) {
;                             const u32x4 ga = *(const u32x4*)(base + off); const u32x4 gs = *(const u32x4*)(X1 + off);
; #pragma unroll
;                             for (int i = 0; i < 4; ++i) { v[2 * i] = bf_lo(ga[i]) + sigm(bf_lo(gs[i])) * v[2 * i]; v[2 * i + 1] = bf_hi(ga[i]) + sigm(bf_hi(gs[i])) * v[2 * i + 1]; }
;                         }
;                         if constexpr (MODE == EPI_OUT_A) {
;                             const f32x4 r0 = *(const f32x4*)(res + off), r1 = *(const f32x4*)(res + off + 4); const u32x4 pl = *(const u32x4*)(X1 + off);
;                             f32x4 o0, o1;
.LBB0_169:
	s_lshl_b32 s4, s18, 8
	s_add_i32 s4, s4, s59
	v_and_or_b32 v145, v140, 15, s4
	v_lshrrev_b32_e32 v140, 1, v140
	v_and_or_b32 v140, v140, 24, s3
	v_or_b32_e32 v162, s60, v140
	v_lshl_add_u64 v[140:141], v[162:163], 1, s[22:23]
	v_mad_i64_i32 v[146:147], s[18:19], s20, v145, 0
	v_lshl_add_u64 v[146:147], v[146:147], 1, v[140:141]
	v_mul_f32_e32 v124, v124, v144
	v_mul_f32_e32 v125, v125, v144
	v_mul_f32_e32 v148, v120, v144
	v_mul_f32_e32 v123, v123, v144
	v_cvt_pk_bf16_f32 v120, v124, v125
	v_mul_f32_e32 v126, v126, v144
	v_mul_f32_e32 v127, v127, v144
	v_mul_f32_e32 v149, v121, v144
	v_mul_f32_e32 v150, v122, v144
	v_cvt_pk_bf16_f32 v121, v126, v127
	v_cvt_pk_bf16_f32 v122, v148, v149
	v_cvt_pk_bf16_f32 v123, v150, v123
	flat_store_dwordx4 v[146:147], v[120:123] nt
	v_mul_f32_e32 v112, v112, v144
	v_mul_f32_e32 v113, v113, v144
	v_mul_f32_e32 v120, v104, v144
	v_mul_f32_e32 v107, v107, v144
	v_cvt_pk_bf16_f32 v104, v112, v113
	v_mul_f32_e32 v114, v114, v144
	v_mul_f32_e32 v115, v115, v144
	v_mul_f32_e32 v121, v105, v144
	v_mul_f32_e32 v122, v106, v144
	v_cvt_pk_bf16_f32 v105, v114, v115
	v_cvt_pk_bf16_f32 v106, v120, v121
	v_cvt_pk_bf16_f32 v107, v122, v107
	flat_store_dwordx4 v[146:147], v[104:107] offset:256 nt
	v_mul_f32_e32 v108, v108, v144
	v_mul_f32_e32 v109, v109, v144
	v_or_b32_e32 v104, 16, v145
	v_mad_i64_i32 v[104:105], s[18:19], s20, v104, 0
	v_lshl_add_u64 v[112:113], v[104:105], 1, v[140:141]
	v_mul_f32_e32 v104, v116, v144
	v_mul_f32_e32 v105, v117, v144
	v_mul_f32_e32 v106, v118, v144
	v_mul_f32_e32 v107, v119, v144
	v_cvt_pk_bf16_f32 v104, v104, v105
	v_mul_f32_e32 v110, v110, v144
	v_mul_f32_e32 v111, v111, v144
	v_cvt_pk_bf16_f32 v105, v106, v107
	v_cvt_pk_bf16_f32 v106, v108, v109
	v_cvt_pk_bf16_f32 v107, v110, v111
	flat_store_dwordx4 v[112:113], v[104:107] nt
	v_mul_f32_e32 v96, v96, v144
	v_mul_f32_e32 v97, v97, v144
	v_mul_f32_e32 v104, v88, v144
	v_mul_f32_e32 v91, v91, v144
	v_cvt_pk_bf16_f32 v88, v96, v97
	v_mul_f32_e32 v98, v98, v144
	v_mul_f32_e32 v99, v99, v144
	v_mul_f32_e32 v105, v89, v144
	v_mul_f32_e32 v106, v90, v144
	v_cvt_pk_bf16_f32 v89, v98, v99
	v_cvt_pk_bf16_f32 v90, v104, v105
	v_cvt_pk_bf16_f32 v91, v106, v91
	flat_store_dwordx4 v[112:113], v[88:91] offset:256 nt
	v_mul_f32_e32 v92, v92, v144
	v_mul_f32_e32 v93, v93, v144
	v_or_b32_e32 v88, 32, v145
	v_mad_i64_i32 v[88:89], s[18:19], s20, v88, 0
	v_lshl_add_u64 v[96:97], v[88:89], 1, v[140:141]
	v_mul_f32_e32 v88, v100, v144
	v_mul_f32_e32 v89, v101, v144
	v_mul_f32_e32 v90, v102, v144
	v_mul_f32_e32 v91, v103, v144
	v_cvt_pk_bf16_f32 v88, v88, v89
	v_mul_f32_e32 v94, v94, v144
	v_mul_f32_e32 v95, v95, v144
	v_cvt_pk_bf16_f32 v89, v90, v91
	v_cvt_pk_bf16_f32 v90, v92, v93
	v_cvt_pk_bf16_f32 v91, v94, v95
	flat_store_dwordx4 v[96:97], v[88:91] nt
	v_mul_f32_e32 v80, v80, v144
	v_mul_f32_e32 v81, v81, v144
	v_mul_f32_e32 v88, v72, v144
	v_mul_f32_e32 v75, v75, v144
	v_cvt_pk_bf16_f32 v72, v80, v81
	v_mul_f32_e32 v82, v82, v144
	v_mul_f32_e32 v83, v83, v144
	v_mul_f32_e32 v89, v73, v144
	v_mul_f32_e32 v90, v74, v144
	v_cvt_pk_bf16_f32 v73, v82, v83
	v_cvt_pk_bf16_f32 v74, v88, v89
	v_cvt_pk_bf16_f32 v75, v90, v75
	flat_store_dwordx4 v[96:97], v[72:75] offset:256 nt
	v_mul_f32_e32 v76, v76, v144
	v_mul_f32_e32 v77, v77, v144
	v_or_b32_e32 v72, 48, v145
	v_mad_i64_i32 v[72:73], s[18:19], s20, v72, 0
	v_lshl_add_u64 v[80:81], v[72:73], 1, v[140:141]
	v_mul_f32_e32 v72, v84, v144
	v_mul_f32_e32 v73, v85, v144
	v_mul_f32_e32 v74, v86, v144
	v_mul_f32_e32 v75, v87, v144
	v_cvt_pk_bf16_f32 v72, v72, v73
	v_mul_f32_e32 v78, v78, v144
	v_mul_f32_e32 v79, v79, v144
	v_cvt_pk_bf16_f32 v73, v74, v75
	v_cvt_pk_bf16_f32 v74, v76, v77
	v_cvt_pk_bf16_f32 v75, v78, v79
	flat_store_dwordx4 v[80:81], v[72:75] nt
	v_mul_f32_e32 v68, v68, v144
	v_mul_f32_e32 v69, v69, v144
	v_mul_f32_e32 v72, v64, v144
	v_mul_f32_e32 v67, v67, v144
	v_cvt_pk_bf16_f32 v64, v68, v69
	v_mul_f32_e32 v70, v70, v144
	v_mul_f32_e32 v71, v71, v144
	v_mul_f32_e32 v73, v65, v144
	v_mul_f32_e32 v74, v66, v144
	v_cvt_pk_bf16_f32 v65, v70, v71
	v_cvt_pk_bf16_f32 v66, v72, v73
; __device__ __forceinline__ float bf_lo(unsigned w) { return __uint_as_float(w << 16); }
;     __device__ __forceinline__ void operator()(const f32x4 (&acc)[2][2][4][2], const pg8::Unit& u, int wr, int wc, int fr_, int fq_) const {
;     ...
;             const int row0 = u.pm * 256 + wr * 64 + fr, col0 = colt + wc * 32 + 8 * fq;
; #pragma unroll
;             for (int ai = 0; ai < 2; ++ai)
; #pragma unroll
;                 for (int m = 0; m < 4; ++m) { const size_t roff = (size_t)(row0 + ai * 128 + m * 16) * ld + col0;
; #pragma unroll
;                     for (int bj = 0; bj < 2; ++bj) { f32x4 v0 = acc[ai][bj][m][0], v1 = acc[ai][bj][m][1]; const size_t off = roff + bj * 128;
;                         float v[8] = {v0[0], v0[1], v0[2], v0[3], v1[0], v1[1], v1[2], v1[3]};
;                         if constexpr (MODE == EPI_INPROJ) {
; #pragma unroll
;                             for (int i = 0; i < 8; ++i) v[i] *= sc;
;                         }
;                         if constexpr (MODE == EPI_GLU) {
;                             const u32x4 yg = *(const u32x4*)(X1 + off); const u32x4 zs = *(const u32x4*)(base + off);
; #pragma unroll
;                             for (int i = 0; i < 4; ++i) { v[2 * i] = bf_lo(yg[i]) * sigm(v[2 * i] * sc_all) * silu(bf_lo(zs[i])); v[2 * i + 1] = bf_hi(yg[i]) * sigm(v[2 * i + 1] * sc_all) * silu(bf_hi(zs[i])); }
;                         }
;                         if constexpr (MODE == EPI_MRG_A) {
;                             const u32x4 ga = *(const u32x4*)(base + off);
; #pragma unroll
;                             for (int i = 0; i < 4; ++i) { v[2 * i] *= sigm(bf_lo(ga[i])); v[2 * i + 1] *= sigm(bf_hi(ga[i])); }
;                         }
;                         if constexpr (MODE == EPI_MRG_B) {
;                             const u32x4 ga = *(const u32x4*)(base + off); const u32x4 gs = *(const u32x4*)(X1 + off);
; #pragma unroll
;                             for (int i = 0; i < 4; ++i) { v[2 * i] = bf_lo(ga[i]) + sigm(bf_lo(gs[i])) * v[2 * i]; v[2 * i + 1] = bf_hi(ga[i]) + sigm(bf_hi(gs[i])) * v[2 * i + 1]; }
;                         }
;                         if constexpr (MODE == EPI_OUT_A) {
;                             const f32x4 r0 = *(const f32x4*)(res + off), r1 = *(const f32x4*)(res + off + 4); const u32x4 pl = *(const u32x4*)(X1 + off);
;                             f32x4 o0, o1;
	v_cvt_pk_bf16_f32 v67, v74, v67
	flat_store_dwordx4 v[80:81], v[64:67] offset:256 nt
	v_mul_f32_e32 v60, v60, v144
	v_mul_f32_e32 v61, v61, v144
	v_add_u32_e32 v64, 0x80, v145
	v_mad_i64_i32 v[64:65], s[18:19], s20, v64, 0
	v_lshl_add_u64 v[64:65], v[64:65], 1, v[140:141]
	v_mul_f32_e32 v66, v56, v144
	v_mul_f32_e32 v59, v59, v144
	v_cvt_pk_bf16_f32 v56, v60, v61
	v_mul_f32_e32 v62, v62, v144
	v_mul_f32_e32 v63, v63, v144
	v_mul_f32_e32 v67, v57, v144
	v_mul_f32_e32 v68, v58, v144
	v_cvt_pk_bf16_f32 v57, v62, v63
	v_cvt_pk_bf16_f32 v58, v66, v67
	v_cvt_pk_bf16_f32 v59, v68, v59
	flat_store_dwordx4 v[64:65], v[56:59] nt
	v_mul_f32_e32 v48, v48, v144
	v_mul_f32_e32 v49, v49, v144
	v_mul_f32_e32 v56, v40, v144
	v_mul_f32_e32 v43, v43, v144
	v_cvt_pk_bf16_f32 v40, v48, v49
	v_mul_f32_e32 v50, v50, v144
	v_mul_f32_e32 v51, v51, v144
	v_mul_f32_e32 v57, v41, v144
	v_mul_f32_e32 v58, v42, v144
	v_cvt_pk_bf16_f32 v41, v50, v51
	v_cvt_pk_bf16_f32 v42, v56, v57
	v_cvt_pk_bf16_f32 v43, v58, v43
	flat_store_dwordx4 v[64:65], v[40:43] offset:256 nt
	v_mul_f32_e32 v44, v44, v144
	v_mul_f32_e32 v45, v45, v144
	v_add_u32_e32 v40, 0x90, v145
	v_mad_i64_i32 v[40:41], s[18:19], s20, v40, 0
	v_lshl_add_u64 v[48:49], v[40:41], 1, v[140:141]
	v_mul_f32_e32 v40, v52, v144
	v_mul_f32_e32 v41, v53, v144
	v_mul_f32_e32 v42, v54, v144
	v_mul_f32_e32 v43, v55, v144
	v_cvt_pk_bf16_f32 v40, v40, v41
	v_mul_f32_e32 v46, v46, v144
	v_mul_f32_e32 v47, v47, v144
	v_cvt_pk_bf16_f32 v41, v42, v43
	v_cvt_pk_bf16_f32 v42, v44, v45
	v_cvt_pk_bf16_f32 v43, v46, v47
	flat_store_dwordx4 v[48:49], v[40:43] nt
	v_mul_f32_e32 v32, v32, v144
	v_mul_f32_e32 v33, v33, v144
	v_mul_f32_e32 v40, v24, v144
	v_mul_f32_e32 v27, v27, v144
	v_cvt_pk_bf16_f32 v24, v32, v33
	v_mul_f32_e32 v34, v34, v144
	v_mul_f32_e32 v35, v35, v144
	v_mul_f32_e32 v41, v25, v144
	v_mul_f32_e32 v42, v26, v144
	v_cvt_pk_bf16_f32 v25, v34, v35
	v_cvt_pk_bf16_f32 v26, v40, v41
	v_cvt_pk_bf16_f32 v27, v42, v27
	flat_store_dwordx4 v[48:49], v[24:27] offset:256 nt
	v_mul_f32_e32 v28, v28, v144
	v_mul_f32_e32 v29, v29, v144
	v_add_u32_e32 v24, 0xa0, v145
	v_mad_i64_i32 v[24:25], s[18:19], s20, v24, 0
	v_lshl_add_u64 v[32:33], v[24:25], 1, v[140:141]
	v_mul_f32_e32 v24, v36, v144
	v_mul_f32_e32 v25, v37, v144
	v_mul_f32_e32 v26, v38, v144
	v_mul_f32_e32 v27, v39, v144
	v_cvt_pk_bf16_f32 v24, v24, v25
	v_mul_f32_e32 v30, v30, v144
	v_mul_f32_e32 v31, v31, v144
	v_cvt_pk_bf16_f32 v25, v26, v27
	v_cvt_pk_bf16_f32 v26, v28, v29
	v_cvt_pk_bf16_f32 v27, v30, v31
	flat_store_dwordx4 v[32:33], v[24:27] nt
	v_mul_f32_e32 v16, v16, v144
	v_mul_f32_e32 v17, v17, v144
	v_mul_f32_e32 v24, v8, v144
	v_mul_f32_e32 v11, v11, v144
	v_cvt_pk_bf16_f32 v8, v16, v17
	v_mul_f32_e32 v18, v18, v144
	v_mul_f32_e32 v19, v19, v144
	v_mul_f32_e32 v25, v9, v144
	v_mul_f32_e32 v26, v10, v144
	v_cvt_pk_bf16_f32 v9, v18, v19
	v_cvt_pk_bf16_f32 v10, v24, v25
	v_cvt_pk_bf16_f32 v11, v26, v11
	flat_store_dwordx4 v[32:33], v[8:11] offset:256 nt
	v_mul_f32_e32 v12, v12, v144
	v_mul_f32_e32 v13, v13, v144
	v_add_u32_e32 v8, 0xb0, v145
	v_mad_i64_i32 v[8:9], s[18:19], s20, v8, 0
	v_lshl_add_u64 v[16:17], v[8:9], 1, v[140:141]
	v_mul_f32_e32 v8, v20, v144
	v_mul_f32_e32 v9, v21, v144
	v_mul_f32_e32 v10, v22, v144
	v_mul_f32_e32 v11, v23, v144
	v_cvt_pk_bf16_f32 v8, v8, v9
	v_cvt_pk_bf16_f32 v9, v10, v11
	v_cvt_pk_bf16_f32 v10, v12, v13
	v_mul_f32_e32 v3, v3, v144
	s_andn2_b64 vcc, exec, s[36:37]
	s_mov_b64 s[18:19], -1
	v_mul_f32_e32 v14, v14, v144
	v_mul_f32_e32 v15, v15, v144
	v_cvt_pk_bf16_f32 v11, v14, v15
	flat_store_dwordx4 v[16:17], v[8:11] nt
	v_mul_f32_e32 v4, v4, v144
	v_mul_f32_e32 v5, v5, v144
	v_mul_f32_e32 v6, v6, v144
	v_mul_f32_e32 v7, v7, v144
	v_mul_f32_e32 v8, v0, v144
	v_mul_f32_e32 v9, v1, v144
	v_mul_f32_e32 v10, v2, v144
	v_cvt_pk_bf16_f32 v0, v4, v5
	v_cvt_pk_bf16_f32 v1, v6, v7
	v_cvt_pk_bf16_f32 v2, v8, v9
	v_cvt_pk_bf16_f32 v3, v10, v3
	flat_store_dwordx4 v[16:17], v[0:3] offset:256 nt
	s_cbranch_vccnz .LBB0_149
	s_andn2_b64 vcc, exec, s[6:7]
	s_cbranch_vccnz .LBB0_148
	s_barrier
	s_branch .LBB0_148
